# MLA row sums moved from 32 v_add_f32 per item to 4 v_mfma_f32_16x16x32_bf16 (ones selector x bf16 P, f32 accumulate) as the diff branch does
# speedup vs baseline: 1.0562x; 1.0007x over previous
.LBB0_489:
	v_mov_b32_e32 v224, 0
	v_mov_b32_e32 v225, 0
	v_mov_b32_e32 v226, 0
	v_mov_b32_e32 v227, 0
	v_and_b32_e32 v228, 31, v1
	v_mov_b32_e32 v229, 0x3f803f80
	v_cmp_eq_u32_e64 s[98:99], 0, v228
	s_nop 1
	v_cndmask_b32_e64 v220, 0, v229, s[98:99]
	v_cmp_eq_u32_e64 s[98:99], 17, v228
	s_nop 1
	v_cndmask_b32_e64 v220, v220, v229, s[98:99]
	v_mov_b32_e32 v221, v220
	v_mov_b32_e32 v222, v220
	v_mov_b32_e32 v223, v220
	s_add_i32 s10, s2, -8
	s_mul_i32 s44, s10, 0x180000
	s_mul_hi_u32 s43, s10, 0x180000
	s_add_u32 s28, s34, s44
	s_addc_u32 s29, s35, s43
	s_add_u32 s0, s38, s44
	s_addc_u32 s1, s39, s43
	s_mov_b32 s11, s8
	s_add_u32 s7, s0, 0x1800000
	s_addc_u32 s26, s1, 0
	s_lshl_b64 s[40:41], s[10:11], 20
	s_add_u32 s0, s69, s40
	s_addc_u32 s1, s70, s41
	s_lshl_b32 s6, s42, 3
	s_add_i32 s6, s3, s6
	v_bfe_u32 v0, v1, 5, 1
	s_mul_hi_i32 s9, s6, 12
	s_mul_i32 s6, s6, 12
	v_lshlrev_b32_e32 v4, 4, v1
	v_or_b32_e32 v2, s6, v0
	v_mov_b32_e32 v3, s9
	v_and_b32_e32 v172, 0x1f0, v4
	v_lshl_add_u64 v[4:5], s[28:29], 0, v[172:173]
	v_lshlrev_b64 v[2:3], 9, v[2:3]
	v_lshl_add_u64 v[2:3], v[4:5], 0, v[2:3]
	global_load_dwordx4 v[118:121], v[2:3], off nt
	global_load_dwordx4 v[114:117], v[2:3], off offset:1024 nt
	global_load_dwordx4 v[110:113], v[2:3], off offset:2048 nt
	global_load_dwordx4 v[106:109], v[2:3], off offset:3072 nt
	v_add_co_u32_e32 v2, vcc, 0x1000, v2
	v_and_b32_e32 v1, 63, v1
	s_nop 0
	v_addc_co_u32_e32 v3, vcc, 0, v3, vcc
	global_load_dwordx4 v[102:105], v[2:3], off nt
	global_load_dwordx4 v[98:101], v[2:3], off offset:1024 nt
	v_lshlrev_b32_e32 v170, 4, v1
	s_andn2_b64 vcc, exec, s[14:15]
	s_mov_b64 s[14:15], -1
	s_cbranch_vccnz .LBB0_491
	s_lshl_b32 s6, s3, 10
	s_and_b32 s6, s6, 0xc00
	s_add_u32 s14, s7, s6
	s_addc_u32 s15, s26, 0
	s_add_i32 s9, s6, 0
	s_mov_b32 m0, s9
	s_nop 0
	global_load_lds_dwordx4 v170, s[14:15]
	s_or_b32 s11, s6, 0x1000
	s_add_u32 s28, s7, s11
	s_addc_u32 s29, s26, 0
	s_mov_b32 m0, s11
	s_nop 0
	global_load_lds_dwordx4 v170, s[28:29]
	s_or_b32 s11, s6, 0x2000
	s_add_u32 s28, s7, s11
	s_addc_u32 s29, s26, 0
	s_mov_b32 m0, s11
	s_nop 0
	global_load_lds_dwordx4 v170, s[28:29]
	s_or_b32 s11, s6, 0x3000
	s_add_u32 s13, s0, s11
	s_addc_u32 s27, s1, 0
	s_add_u32 s28, s13, 0xffffd000
	s_addc_u32 s29, s27, -1
	s_mov_b32 m0, s11
	s_nop 0
	global_load_lds_dwordx4 v170, s[28:29]
	s_or_b32 s11, s6, 0x4000
	s_add_u32 s13, s0, s11
	s_addc_u32 s27, s1, 0
	s_add_u32 s28, s13, 0xffffd000
	s_addc_u32 s29, s27, -1
	s_mov_b32 m0, s11
	s_nop 0
	global_load_lds_dwordx4 v170, s[28:29]
	s_add_u32 s28, s14, 0x3000
	s_addc_u32 s29, s15, 0
	s_add_i32 s11, s9, 0x5000
	s_mov_b32 m0, s11
	s_nop 0
	global_load_lds_dwordx4 v170, s[28:29]
	s_add_u32 s28, s14, 0x4000
	s_addc_u32 s29, s15, 0
	s_add_i32 s11, s9, 0x6000
	s_mov_b32 m0, s11
	s_nop 0
	global_load_lds_dwordx4 v170, s[28:29]
	s_add_u32 s28, s14, 0x5000
	s_addc_u32 s29, s15, 0
	s_add_i32 s11, s9, 0x7000
	s_add_u32 s6, s0, s6
	s_mov_b32 m0, s11
	s_nop 0
	global_load_lds_dwordx4 v170, s[28:29]
	s_addc_u32 s11, s1, 0
	s_add_u32 s28, s6, 0x2000
	s_addc_u32 s29, s11, 0
	s_add_i32 s13, s9, 0x8000
	s_mov_b32 m0, s13
	s_nop 0
	global_load_lds_dwordx4 v170, s[28:29]
	s_add_u32 s28, s6, 0x3000
	s_addc_u32 s29, s11, 0
	s_add_i32 s13, s9, 0x9000
	s_mov_b32 m0, s13
	s_nop 0
	global_load_lds_dwordx4 v170, s[28:29]
	s_add_u32 s28, s14, 0x6000
	s_addc_u32 s29, s15, 0
	s_add_i32 s13, s9, 0xa000
	s_mov_b32 m0, s13
	s_nop 0
	global_load_lds_dwordx4 v170, s[28:29]
	s_add_u32 s28, s14, 0x7000
	s_addc_u32 s29, s15, 0
	s_add_i32 s13, s9, 0xb000
	s_mov_b32 m0, s13
	s_nop 0
	global_load_lds_dwordx4 v170, s[28:29]
	s_add_u32 s28, s14, 0x8000
	s_addc_u32 s29, s15, 0
	s_add_i32 s13, s9, 0xc000
	s_mov_b32 m0, s13
	s_nop 0
	global_load_lds_dwordx4 v170, s[28:29]
	s_add_u32 s28, s6, 0x4000
	s_addc_u32 s29, s11, 0
	s_add_i32 s13, s9, 0xd000
	s_mov_b32 m0, s13
	s_nop 0
	global_load_lds_dwordx4 v170, s[28:29]
	s_add_u32 s28, s6, 0x5000
	s_addc_u32 s29, s11, 0
	s_add_i32 s13, s9, 0xe000
	s_mov_b32 m0, s13
	s_nop 0
	global_load_lds_dwordx4 v170, s[28:29]
	s_add_u32 s28, s14, 0x9000
	s_addc_u32 s29, s15, 0
	s_add_i32 s13, s9, 0xf000
	s_mov_b32 m0, s13
	s_nop 0
	global_load_lds_dwordx4 v170, s[28:29]
	s_add_u32 s28, s14, 0xa000
	s_addc_u32 s29, s15, 0
	s_add_i32 s13, s9, 0x10000
	s_add_u32 s14, s14, 0xb000
	s_mov_b32 m0, s13
	s_nop 0
	global_load_lds_dwordx4 v170, s[28:29]
	s_addc_u32 s15, s15, 0
	s_add_i32 s13, s9, 0x11000
	s_mov_b32 m0, s13
	s_nop 0
	global_load_lds_dwordx4 v170, s[14:15]
	s_add_u32 s14, s6, 0x6000
	s_addc_u32 s15, s11, 0
	s_add_i32 s13, s9, 0x12000
	s_mov_b32 m0, s13
	s_nop 0
	global_load_lds_dwordx4 v170, s[14:15]
	s_add_u32 s14, s6, 0x7000
	s_addc_u32 s15, s11, 0
	s_add_i32 s9, s9, 0x13000
	s_mov_b32 m0, s9
	s_nop 0
	global_load_lds_dwordx4 v170, s[14:15]
	s_waitcnt vmcnt(10) lgkmcnt(0)
	s_barrier
	s_mov_b64 s[14:15], 0

.LBB0_500:
	s_mul_hi_u32 s9, s51, 0xaaaaaaab
	s_lshr_b32 s9, s9, 2
	s_mul_i32 s9, s9, 0xfffe2000
	s_add_i32 s9, s9, 0
	v_add_u32_e32 v141, s50, v139
	v_add_u32_e32 v140, s9, v141
	ds_read_b128 v[34:37], v140 offset:12288
	ds_read_b128 v[38:41], v140 offset:12800
	ds_read_b128 v[42:45], v140 offset:20480
	ds_read_b128 v[46:49], v140 offset:20992
	ds_read_b128 v[142:145], v140 offset:22528
	s_mul_hi_u32 s9, s48, 0xaaaaaaab
	s_lshr_b32 s9, s9, 2
	s_mul_i32 s9, s9, 0xfffe2000
	s_add_i32 s52, s9, 0
	v_exp_f32_e32 v18, v18
	v_exp_f32_e32 v19, v19
	v_exp_f32_e32 v20, v20
	v_exp_f32_e32 v21, v21
	v_exp_f32_e32 v22, v22
	v_exp_f32_e32 v23, v23
	v_exp_f32_e32 v24, v24
	v_exp_f32_e32 v25, v25
	v_cvt_pk_bf16_f32 v134, v18, v19
	v_cvt_pk_bf16_f32 v135, v20, v21
	v_cvt_pk_bf16_f32 v136, v22, v23
	v_cvt_pk_bf16_f32 v137, v24, v25
	s_waitcnt lgkmcnt(3)
	s_nop 0
	v_mfma_f32_32x32x16_bf16 v[66:81], v[34:37], v[134:137], v[66:81]
	ds_read_b128 v[146:149], v140 offset:14336
	v_exp_f32_e32 v26, v26
	v_exp_f32_e32 v27, v27
	v_mfma_f32_32x32x16_bf16 v[82:97], v[38:41], v[134:137], v[82:97]
	ds_read_b128 v[150:153], v140 offset:14848
	v_exp_f32_e32 v28, v28
	v_exp_f32_e32 v29, v29
	v_mfma_f32_16x16x32_bf16 v[224:227], v[220:223], v[134:137], v[224:227]
	v_exp_f32_e32 v30, v30
	v_exp_f32_e32 v31, v31
	ds_read_b128 v[154:157], v140 offset:23040
	v_exp_f32_e32 v32, v32
	v_exp_f32_e32 v33, v33
	s_waitcnt lgkmcnt(4)
	v_mfma_f32_32x32x16_bf16 v[50:65], v[42:45], v[118:121], 0
	ds_read_b128 v[158:161], v140 offset:24576
	v_cvt_pk_bf16_f32 v130, v26, v27
	v_cvt_pk_bf16_f32 v131, v28, v29
	v_mfma_f32_32x32x16_bf16 v[34:49], v[46:49], v[118:121], 0
	s_waitcnt lgkmcnt(3)
	v_mfma_f32_32x32x16_bf16 v[50:65], v[142:145], v[114:117], v[50:65]
	ds_read_b128 v[142:145], v140 offset:25088
	v_cvt_pk_bf16_f32 v132, v30, v31
	v_cvt_pk_bf16_f32 v133, v32, v33
	s_nop 1
	v_mfma_f32_32x32x16_bf16 v[66:81], v[146:149], v[130:133], v[66:81]
	ds_read_b128 v[18:21], v140 offset:16384
	v_exp_f32_e32 v2, v2
	v_exp_f32_e32 v3, v3
	s_waitcnt lgkmcnt(3)
	v_mfma_f32_32x32x16_bf16 v[82:97], v[150:153], v[130:133], v[82:97]
	ds_read_b128 v[22:25], v140 offset:16896
	v_exp_f32_e32 v4, v4
	v_exp_f32_e32 v5, v5
	v_mfma_f32_16x16x32_bf16 v[224:227], v[220:223], v[130:133], v[224:227]
	v_exp_f32_e32 v6, v6
	v_exp_f32_e32 v7, v7
	ds_read_b128 v[26:29], v140 offset:26624
	v_exp_f32_e32 v8, v8
	v_exp_f32_e32 v9, v9
	v_mfma_f32_32x32x16_bf16 v[34:49], v[154:157], v[114:117], v[34:49]
	ds_read_b128 v[30:33], v140 offset:27136
	v_cvt_pk_bf16_f32 v134, v2, v3
	v_cvt_pk_bf16_f32 v135, v4, v5
	s_waitcnt lgkmcnt(4)
	v_mfma_f32_32x32x16_bf16 v[50:65], v[158:161], v[110:113], v[50:65]
	v_mfma_f32_32x32x16_bf16 v[34:49], v[142:145], v[110:113], v[34:49]
	ds_read_b128 v[142:145], v140 offset:28672
	v_cvt_pk_bf16_f32 v136, v6, v7
	v_cvt_pk_bf16_f32 v137, v8, v9
	s_waitcnt lgkmcnt(3)
	s_nop 0
	v_mfma_f32_32x32x16_bf16 v[66:81], v[18:21], v[134:137], v[66:81]
	ds_read_b128 v[18:21], v140 offset:18432
	v_exp_f32_e32 v10, v10
	v_exp_f32_e32 v11, v11
	v_mfma_f32_32x32x16_bf16 v[82:97], v[22:25], v[134:137], v[82:97]
	ds_read_b128 v[22:25], v140 offset:18944
	v_exp_f32_e32 v12, v12
	v_exp_f32_e32 v13, v13
	v_mfma_f32_16x16x32_bf16 v[224:227], v[220:223], v[134:137], v[224:227]
	v_exp_f32_e32 v14, v14
	v_exp_f32_e32 v15, v15
	s_waitcnt lgkmcnt(3)
	v_mfma_f32_32x32x16_bf16 v[50:65], v[26:29], v[106:109], v[50:65]
	ds_read_b128 v[26:29], v140 offset:29184
	v_exp_f32_e32 v16, v16
	v_exp_f32_e32 v17, v17
	v_mfma_f32_32x32x16_bf16 v[34:49], v[30:33], v[106:109], v[34:49]
	ds_read_b128 v[30:33], v140 offset:30720
	v_cvt_pk_bf16_f32 v130, v10, v11
	v_cvt_pk_bf16_f32 v131, v12, v13
	s_waitcnt lgkmcnt(3)
	v_mfma_f32_32x32x16_bf16 v[50:65], v[142:145], v[102:105], v[50:65]
	ds_read_b128 v[142:145], v140 offset:31232
	v_cvt_pk_bf16_f32 v132, v14, v15
	v_cvt_pk_bf16_f32 v133, v16, v17
	s_nop 1
	v_mfma_f32_32x32x16_bf16 v[66:81], v[18:21], v[130:133], v[66:81]
	s_waitcnt lgkmcnt(2)
	v_mfma_f32_32x32x16_bf16 v[82:97], v[22:25], v[130:133], v[82:97]
	v_mfma_f32_16x16x32_bf16 v[224:227], v[220:223], v[130:133], v[224:227]
	v_mfma_f32_32x32x16_bf16 v[34:49], v[26:29], v[102:105], v[34:49]
	s_waitcnt lgkmcnt(0)
	v_mfma_f32_32x32x16_bf16 v[50:65], v[30:33], v[98:101], v[50:65]
	v_mfma_f32_32x32x16_bf16 v[34:49], v[142:145], v[98:101], v[34:49]
	v_add_u32_e32 v135, s52, v141
	ds_read_b128 v[2:5], v140 offset:32768
	ds_read_b128 v[6:9], v140 offset:33280
	ds_read_b128 v[10:13], v135 offset:40960
	ds_read_b128 v[14:17], v135 offset:41472
	ds_read_b128 v[142:145], v135 offset:43008
	s_nop 3
	v_exp_f32_e32 v50, v50
	v_exp_f32_e32 v51, v51
	v_exp_f32_e32 v52, v52
	v_exp_f32_e32 v53, v53
	v_exp_f32_e32 v54, v54
	v_exp_f32_e32 v55, v55
	v_exp_f32_e32 v56, v56
	v_exp_f32_e32 v57, v57
	v_cvt_pk_bf16_f32 v130, v50, v51
	v_cvt_pk_bf16_f32 v131, v52, v53
	v_cvt_pk_bf16_f32 v132, v54, v55
	v_cvt_pk_bf16_f32 v133, v56, v57
	s_waitcnt lgkmcnt(3)
	s_nop 0
	v_mfma_f32_32x32x16_bf16 v[66:81], v[2:5], v[130:133], v[66:81]
	ds_read_b128 v[146:149], v140 offset:34816
	v_exp_f32_e32 v58, v58
	v_exp_f32_e32 v59, v59
	v_mfma_f32_32x32x16_bf16 v[82:97], v[6:9], v[130:133], v[82:97]
	ds_read_b128 v[150:153], v140 offset:35328
	v_exp_f32_e32 v60, v60
	v_exp_f32_e32 v61, v61
	v_mfma_f32_16x16x32_bf16 v[224:227], v[220:223], v[130:133], v[224:227]
	v_exp_f32_e32 v62, v62
	v_exp_f32_e32 v63, v63
	s_waitcnt lgkmcnt(3)
	v_mfma_f32_32x32x16_bf16 v[18:33], v[10:13], v[118:121], 0
	ds_read_b128 v[154:157], v135 offset:43520
	v_exp_f32_e32 v64, v64
	v_exp_f32_e32 v65, v65
	v_mfma_f32_32x32x16_bf16 v[2:17], v[14:17], v[118:121], 0
	ds_read_b128 v[158:161], v135 offset:45056
	v_cvt_pk_bf16_f32 v122, v58, v59
	v_cvt_pk_bf16_f32 v123, v60, v61
	s_waitcnt lgkmcnt(3)
	v_mfma_f32_32x32x16_bf16 v[18:33], v[142:145], v[114:117], v[18:33]
	ds_read_b128 v[142:145], v135 offset:45568
	v_cvt_pk_bf16_f32 v124, v62, v63
	v_cvt_pk_bf16_f32 v125, v64, v65
	s_nop 1
	v_mfma_f32_32x32x16_bf16 v[66:81], v[146:149], v[122:125], v[66:81]
	ds_read_b128 v[50:53], v140 offset:36864
	v_exp_f32_e32 v34, v34
	v_exp_f32_e32 v35, v35
	s_waitcnt lgkmcnt(3)
	v_mfma_f32_32x32x16_bf16 v[82:97], v[150:153], v[122:125], v[82:97]
	ds_read_b128 v[54:57], v140 offset:37376
	v_exp_f32_e32 v36, v36
	v_exp_f32_e32 v37, v37
	v_mfma_f32_16x16x32_bf16 v[224:227], v[220:223], v[122:125], v[224:227]
	v_exp_f32_e32 v38, v38
	v_exp_f32_e32 v39, v39
	v_mfma_f32_32x32x16_bf16 v[2:17], v[154:157], v[114:117], v[2:17]
	ds_read_b128 v[58:61], v135 offset:47104
	v_exp_f32_e32 v40, v40
	v_exp_f32_e32 v41, v41
	s_waitcnt lgkmcnt(3)
	v_mfma_f32_32x32x16_bf16 v[18:33], v[158:161], v[110:113], v[18:33]
	ds_read_b128 v[62:65], v135 offset:47616
	v_cvt_pk_bf16_f32 v130, v34, v35
	v_cvt_pk_bf16_f32 v131, v36, v37
	v_mfma_f32_32x32x16_bf16 v[2:17], v[142:145], v[110:113], v[2:17]
	ds_read_b128 v[142:145], v135 offset:49152
	v_cvt_pk_bf16_f32 v132, v38, v39
	v_cvt_pk_bf16_f32 v133, v40, v41
	s_waitcnt lgkmcnt(3)
	s_nop 0
	v_mfma_f32_32x32x16_bf16 v[66:81], v[50:53], v[130:133], v[66:81]
	ds_read_b128 v[50:53], v140 offset:38912
	v_exp_f32_e32 v42, v42
	v_exp_f32_e32 v43, v43
	v_mfma_f32_32x32x16_bf16 v[82:97], v[54:57], v[130:133], v[82:97]
	ds_read_b128 v[54:57], v140 offset:39424
	v_exp_f32_e32 v44, v44
	v_exp_f32_e32 v45, v45
	v_mfma_f32_16x16x32_bf16 v[224:227], v[220:223], v[130:133], v[224:227]
	v_exp_f32_e32 v46, v46
	v_exp_f32_e32 v47, v47
	s_waitcnt lgkmcnt(3)
	v_mfma_f32_32x32x16_bf16 v[18:33], v[58:61], v[106:109], v[18:33]
	ds_read_b128 v[58:61], v135 offset:49664
	v_exp_f32_e32 v48, v48
	v_exp_f32_e32 v49, v49
	v_mfma_f32_32x32x16_bf16 v[2:17], v[62:65], v[106:109], v[2:17]
	ds_read_b128 v[62:65], v135 offset:51200
	v_cvt_pk_bf16_f32 v122, v42, v43
	v_cvt_pk_bf16_f32 v123, v44, v45
	s_waitcnt lgkmcnt(3)
	v_mfma_f32_32x32x16_bf16 v[18:33], v[142:145], v[102:105], v[18:33]
	ds_read_b128 v[130:133], v135 offset:51712
	v_cvt_pk_bf16_f32 v124, v46, v47
	v_cvt_pk_bf16_f32 v125, v48, v49
	s_nop 1
	v_mfma_f32_32x32x16_bf16 v[66:81], v[50:53], v[122:125], v[66:81]
	s_waitcnt lgkmcnt(2)
	v_mfma_f32_32x32x16_bf16 v[82:97], v[54:57], v[122:125], v[82:97]
	v_mfma_f32_16x16x32_bf16 v[224:227], v[220:223], v[122:125], v[224:227]
	v_mfma_f32_32x32x16_bf16 v[2:17], v[58:61], v[102:105], v[2:17]
	s_waitcnt lgkmcnt(0)
	v_mfma_f32_32x32x16_bf16 v[18:33], v[62:65], v[98:101], v[18:33]
	v_mfma_f32_32x32x16_bf16 v[2:17], v[130:133], v[98:101], v[2:17]
	s_add_i32 s48, s48, 2
	s_add_i32 s9, s51, 2
	s_add_u32 s29, s29, 0x4000
	s_addc_u32 s30, s30, 0
	s_add_u32 s31, s31, 0x6000
	s_addc_u32 s33, s33, 0
	s_add_i32 s49, s49, 2
	s_add_i32 s50, s50, 0xa000
	s_add_i32 s10, s51, 4
	s_cmp_le_i32 s10, s27
	s_cbranch_scc0 .LBB0_503
	s_mov_b32 s51, s9
	s_branch .LBB0_496

.LBB0_528:
	v_mbcnt_lo_u32_b32 v228, -1, 0
	v_mbcnt_hi_u32_b32 v228, -1, v228
	v_and_b32_e32 v229, 15, v228
	v_lshlrev_b32_e32 v229, 2, v229
	ds_bpermute_b32 v230, v229, v224
	ds_bpermute_b32 v231, v229, v225
	v_and_b32_e32 v228, 16, v228
	v_cmp_ne_u32_e64 s[98:99], 0, v228
	s_waitcnt lgkmcnt(0)
	s_nop 1
	v_cndmask_b32_e64 v230, v230, v231, s[98:99]
	v_mov_b32_e32 v1, v139
	s_nop 1
	v_permlane32_swap_b32_e32 v139, v1
	v_add_f32_e32 v1, v139, v1
	s_add_i32 s34, s34, s45
	v_add_f32_e32 v0, v230, v1
	v_mbcnt_lo_u32_b32 v2, -1, 0
	v_mbcnt_hi_u32_b32 v2, -1, v2
	v_rcp_f32_e32 v6, v0
	v_and_or_b32 v0, v2, 31, s34
	s_mov_b32 s0, s97
	v_ashrrev_i32_e32 v1, 31, v0
	v_lshlrev_b64 v[0:1], 11, v[0:1]
	v_lshl_add_u64 v[0:1], s[58:59], 0, v[0:1]
	s_lshl_b32 s0, s35, 1
	s_mov_b32 s1, s8
	v_lshrrev_b32_e32 v2, 1, v2
	s_waitcnt vmcnt(3)
	v_mov_b32_e32 v7, v136
	v_mov_b32_e32 v8, v137
	s_waitcnt vmcnt(2)
	v_mov_b32_e32 v9, v132
	v_mov_b32_e32 v20, v133
	v_lshl_add_u64 v[0:1], v[0:1], 0, s[0:1]
	v_and_b32_e32 v172, 16, v2
	v_permlane32_swap_b32_e32 v134, v7
	v_permlane32_swap_b32_e32 v135, v8
	v_permlane32_swap_b32_e32 v130, v9
	v_permlane32_swap_b32_e32 v131, v20
	v_lshl_add_u64 v[4:5], v[0:1], 0, v[172:173]
	v_lshlrev_b32_e32 v0, 16, v134
	v_and_b32_e32 v1, 0xffff0000, v134
	v_lshlrev_b32_e32 v18, 16, v8
	v_and_b32_e32 v19, 0xffff0000, v8
	v_lshlrev_b32_e32 v10, 16, v9
	v_and_b32_e32 v11, 0xffff0000, v9
	v_lshlrev_b32_e32 v8, 16, v20
	v_and_b32_e32 v9, 0xffff0000, v20
	v_pk_mul_f32 v[20:21], v[82:83], v[6:7] op_sel_hi:[1,0]
	v_lshlrev_b32_e32 v16, 16, v7
	v_and_b32_e32 v17, 0xffff0000, v7
	v_mul_f32_e32 v7, 0xbfb8aa3b, v0
	v_pk_mul_f32 v[20:21], v[20:21], v[0:1]
	v_mul_f32_e32 v0, 0xbfb8aa3b, v1
	v_exp_f32_e32 v7, v7
	v_exp_f32_e32 v0, v0
	v_lshlrev_b32_e32 v2, 16, v135
	v_and_b32_e32 v3, 0xffff0000, v135
	v_add_f32_e32 v7, 1.0, v7
	v_add_f32_e32 v0, 1.0, v0
	v_rcp_f32_e32 v22, v7
	v_rcp_f32_e32 v23, v0
	v_lshlrev_b32_e32 v14, 16, v130
	v_and_b32_e32 v15, 0xffff0000, v130
	v_lshlrev_b32_e32 v12, 16, v131
	v_pk_mul_f32 v[0:1], v[20:21], v[22:23]
	v_pk_mul_f32 v[20:21], v[84:85], v[6:7] op_sel_hi:[1,0]
	v_mul_f32_e32 v7, 0xbfb8aa3b, v2
	v_pk_mul_f32 v[20:21], v[20:21], v[2:3]
	v_mul_f32_e32 v2, 0xbfb8aa3b, v3
	v_exp_f32_e32 v7, v7
	v_exp_f32_e32 v2, v2
	v_cvt_pk_bf16_f32 v0, v0, v1
	v_and_b32_e32 v13, 0xffff0000, v131
	v_add_f32_e32 v7, 1.0, v7
	v_add_f32_e32 v2, 1.0, v2
	v_rcp_f32_e32 v22, v7
	v_rcp_f32_e32 v23, v2
	s_nop 0
	v_pk_mul_f32 v[2:3], v[20:21], v[22:23]
	s_nop 0
	v_cvt_pk_bf16_f32 v1, v2, v3
	v_pk_mul_f32 v[2:3], v[86:87], v[6:7] op_sel_hi:[1,0]
	v_mul_f32_e32 v7, 0xbfb8aa3b, v16
	v_exp_f32_e32 v7, v7
	v_pk_mul_f32 v[2:3], v[2:3], v[16:17]
	v_add_f32_e32 v7, 1.0, v7
	v_rcp_f32_e32 v20, v7
	v_mul_f32_e32 v7, 0xbfb8aa3b, v17
	v_exp_f32_e32 v7, v7
	s_nop 0
	v_add_f32_e32 v7, 1.0, v7
	v_rcp_f32_e32 v21, v7
	v_pk_mul_f32 v[16:17], v[88:89], v[6:7] op_sel_hi:[1,0]
	v_mul_f32_e32 v7, 0xbfb8aa3b, v18
	v_exp_f32_e32 v7, v7
	v_pk_mul_f32 v[2:3], v[2:3], v[20:21]
	v_pk_mul_f32 v[16:17], v[16:17], v[18:19]
	v_cvt_pk_bf16_f32 v2, v2, v3
	v_add_f32_e32 v7, 1.0, v7
	v_rcp_f32_e32 v20, v7
	v_mul_f32_e32 v7, 0xbfb8aa3b, v19
	v_exp_f32_e32 v7, v7
	v_permlane32_swap_b32_e32 v0, v2
	v_add_f32_e32 v7, 1.0, v7
	v_rcp_f32_e32 v21, v7
	s_nop 0
	v_pk_mul_f32 v[16:17], v[16:17], v[20:21]
	s_nop 0
	v_cvt_pk_bf16_f32 v3, v16, v17
	v_pk_mul_f32 v[16:17], v[90:91], v[6:7] op_sel_hi:[1,0]
	v_mul_f32_e32 v7, 0xbfb8aa3b, v14
	v_exp_f32_e32 v7, v7
	v_pk_mul_f32 v[16:17], v[16:17], v[14:15]
	s_waitcnt vmcnt(0)
	v_mov_b32_e32 v20, v125
	v_permlane32_swap_b32_e32 v1, v3
	v_add_f32_e32 v7, 1.0, v7
	v_rcp_f32_e32 v18, v7
	v_mul_f32_e32 v7, 0xbfb8aa3b, v15
	v_exp_f32_e32 v7, v7
	v_permlane32_swap_b32_e32 v123, v20
	global_store_dwordx4 v[4:5], v[0:3], off
	v_add_f32_e32 v7, 1.0, v7
	v_rcp_f32_e32 v19, v7
	s_nop 0
	v_pk_mul_f32 v[14:15], v[16:17], v[18:19]
	v_pk_mul_f32 v[16:17], v[92:93], v[6:7] op_sel_hi:[1,0]
	v_mul_f32_e32 v7, 0xbfb8aa3b, v12
	v_exp_f32_e32 v7, v7
	v_pk_mul_f32 v[16:17], v[16:17], v[12:13]
	v_cvt_pk_bf16_f32 v12, v14, v15
	v_add_f32_e32 v7, 1.0, v7
	v_rcp_f32_e32 v18, v7
	v_mul_f32_e32 v7, 0xbfb8aa3b, v13
	v_exp_f32_e32 v7, v7
	s_nop 0
	v_add_f32_e32 v7, 1.0, v7
	v_rcp_f32_e32 v19, v7
	v_pk_mul_f32 v[14:15], v[94:95], v[6:7] op_sel_hi:[1,0]
	v_mul_f32_e32 v7, 0xbfb8aa3b, v10
	v_exp_f32_e32 v7, v7
	v_pk_mul_f32 v[16:17], v[16:17], v[18:19]
	v_pk_mul_f32 v[14:15], v[14:15], v[10:11]
	v_cvt_pk_bf16_f32 v13, v16, v17
	v_add_f32_e32 v7, 1.0, v7
	v_rcp_f32_e32 v16, v7
	v_mul_f32_e32 v7, 0xbfb8aa3b, v11
	v_exp_f32_e32 v7, v7
	s_nop 0
	v_add_f32_e32 v7, 1.0, v7
	v_rcp_f32_e32 v17, v7
	s_nop 0
	v_pk_mul_f32 v[10:11], v[14:15], v[16:17]
	v_pk_mul_f32 v[14:15], v[96:97], v[6:7] op_sel_hi:[1,0]
	v_mul_f32_e32 v7, 0xbfb8aa3b, v8
	v_exp_f32_e32 v7, v7
	v_pk_mul_f32 v[14:15], v[14:15], v[8:9]
	v_add_f32_e32 v7, 1.0, v7
	v_rcp_f32_e32 v16, v7
	v_mul_f32_e32 v7, 0xbfb8aa3b, v9
	v_exp_f32_e32 v7, v7
	s_nop 0
	v_add_f32_e32 v7, 1.0, v7
	v_rcp_f32_e32 v17, v7
	v_mov_b32_e32 v7, v128
	s_nop 1
	v_permlane32_swap_b32_e32 v126, v7
	v_pk_mul_f32 v[8:9], v[14:15], v[16:17]
	v_cvt_pk_bf16_f32 v14, v10, v11
	v_cvt_pk_bf16_f32 v15, v8, v9
	v_mov_b32_e32 v8, v129
	v_mov_b32_e32 v9, v124
	s_nop 0
	v_permlane32_swap_b32_e32 v127, v8
	v_permlane32_swap_b32_e32 v122, v9
	v_lshlrev_b32_e32 v0, 16, v126
	v_and_b32_e32 v1, 0xffff0000, v126
	v_lshlrev_b32_e32 v18, 16, v8
	v_and_b32_e32 v19, 0xffff0000, v8
	v_lshlrev_b32_e32 v10, 16, v9
	v_and_b32_e32 v11, 0xffff0000, v9
	v_lshlrev_b32_e32 v8, 16, v20
	v_and_b32_e32 v9, 0xffff0000, v20
	v_pk_mul_f32 v[20:21], v[66:67], v[6:7] op_sel_hi:[1,0]
	v_lshlrev_b32_e32 v16, 16, v7
	v_and_b32_e32 v17, 0xffff0000, v7
	v_mul_f32_e32 v7, 0xbfb8aa3b, v0
	v_pk_mul_f32 v[20:21], v[20:21], v[0:1]
	v_mul_f32_e32 v0, 0xbfb8aa3b, v1
	v_exp_f32_e32 v7, v7
	v_exp_f32_e32 v0, v0
	v_lshlrev_b32_e32 v2, 16, v127
	v_and_b32_e32 v3, 0xffff0000, v127
	v_add_f32_e32 v7, 1.0, v7
	v_add_f32_e32 v0, 1.0, v0
	v_rcp_f32_e32 v22, v7
	v_rcp_f32_e32 v23, v0
	v_permlane32_swap_b32_e32 v12, v14
	v_permlane32_swap_b32_e32 v13, v15
	v_pk_mul_f32 v[0:1], v[20:21], v[22:23]
	v_pk_mul_f32 v[20:21], v[68:69], v[6:7] op_sel_hi:[1,0]
	v_mul_f32_e32 v7, 0xbfb8aa3b, v2
	v_pk_mul_f32 v[20:21], v[20:21], v[2:3]
	v_mul_f32_e32 v2, 0xbfb8aa3b, v3
	v_exp_f32_e32 v7, v7
	v_exp_f32_e32 v2, v2
	v_cvt_pk_bf16_f32 v0, v0, v1
	global_store_dwordx4 v[4:5], v[12:15], off offset:32
	v_add_f32_e32 v7, 1.0, v7
	v_add_f32_e32 v2, 1.0, v2
	v_rcp_f32_e32 v22, v7
	v_rcp_f32_e32 v23, v2
	v_lshlrev_b32_e32 v14, 16, v122
	v_and_b32_e32 v15, 0xffff0000, v122
	v_lshlrev_b32_e32 v12, 16, v123
	v_pk_mul_f32 v[2:3], v[20:21], v[22:23]
	v_and_b32_e32 v13, 0xffff0000, v123
	v_cvt_pk_bf16_f32 v1, v2, v3
	v_pk_mul_f32 v[2:3], v[70:71], v[6:7] op_sel_hi:[1,0]
	v_mul_f32_e32 v7, 0xbfb8aa3b, v16
	v_exp_f32_e32 v7, v7
	v_pk_mul_f32 v[2:3], v[2:3], v[16:17]
	v_add_f32_e32 v7, 1.0, v7
	v_rcp_f32_e32 v20, v7
	v_mul_f32_e32 v7, 0xbfb8aa3b, v17
	v_exp_f32_e32 v7, v7
	s_nop 0
	v_add_f32_e32 v7, 1.0, v7
	v_rcp_f32_e32 v21, v7
	v_pk_mul_f32 v[16:17], v[72:73], v[6:7] op_sel_hi:[1,0]
	v_mul_f32_e32 v7, 0xbfb8aa3b, v18
	v_exp_f32_e32 v7, v7
	v_pk_mul_f32 v[2:3], v[2:3], v[20:21]
	v_pk_mul_f32 v[16:17], v[16:17], v[18:19]
	v_cvt_pk_bf16_f32 v2, v2, v3
	v_add_f32_e32 v7, 1.0, v7
	v_rcp_f32_e32 v20, v7
	v_mul_f32_e32 v7, 0xbfb8aa3b, v19
	v_exp_f32_e32 v7, v7
	v_permlane32_swap_b32_e32 v0, v2
	v_add_f32_e32 v7, 1.0, v7
	v_rcp_f32_e32 v21, v7
	s_nop 0
	v_pk_mul_f32 v[16:17], v[16:17], v[20:21]
	s_nop 0
	v_cvt_pk_bf16_f32 v3, v16, v17
	v_pk_mul_f32 v[16:17], v[74:75], v[6:7] op_sel_hi:[1,0]
	v_mul_f32_e32 v7, 0xbfb8aa3b, v14
	v_exp_f32_e32 v7, v7
	v_pk_mul_f32 v[16:17], v[16:17], v[14:15]
	v_permlane32_swap_b32_e32 v1, v3
	v_add_f32_e32 v7, 1.0, v7
	v_rcp_f32_e32 v18, v7
	v_mul_f32_e32 v7, 0xbfb8aa3b, v15
	v_exp_f32_e32 v7, v7
	global_store_dwordx4 v[4:5], v[0:3], off offset:64
	v_add_f32_e32 v7, 1.0, v7
	v_rcp_f32_e32 v19, v7
	s_nop 0
	v_pk_mul_f32 v[14:15], v[16:17], v[18:19]
	v_pk_mul_f32 v[16:17], v[76:77], v[6:7] op_sel_hi:[1,0]
	v_mul_f32_e32 v7, 0xbfb8aa3b, v12
	v_exp_f32_e32 v7, v7
	v_pk_mul_f32 v[16:17], v[16:17], v[12:13]
	v_cvt_pk_bf16_f32 v12, v14, v15
	v_add_f32_e32 v7, 1.0, v7
	v_rcp_f32_e32 v18, v7
	v_mul_f32_e32 v7, 0xbfb8aa3b, v13
	v_exp_f32_e32 v7, v7
	s_nop 0
	v_add_f32_e32 v7, 1.0, v7
	v_rcp_f32_e32 v19, v7
	v_pk_mul_f32 v[14:15], v[78:79], v[6:7] op_sel_hi:[1,0]
	v_mul_f32_e32 v7, 0xbfb8aa3b, v10
	v_exp_f32_e32 v7, v7
	v_pk_mul_f32 v[16:17], v[16:17], v[18:19]
	v_pk_mul_f32 v[14:15], v[14:15], v[10:11]
	v_cvt_pk_bf16_f32 v13, v16, v17
	v_add_f32_e32 v7, 1.0, v7
	v_rcp_f32_e32 v16, v7
	v_mul_f32_e32 v7, 0xbfb8aa3b, v11
	v_exp_f32_e32 v7, v7
	s_nop 0
	v_add_f32_e32 v7, 1.0, v7
	v_rcp_f32_e32 v17, v7
	v_pk_mul_f32 v[6:7], v[80:81], v[6:7] op_sel_hi:[1,0]
	v_pk_mul_f32 v[10:11], v[14:15], v[16:17]
	v_mul_f32_e32 v14, 0xbfb8aa3b, v8
	v_pk_mul_f32 v[6:7], v[6:7], v[8:9]
	v_mul_f32_e32 v8, 0xbfb8aa3b, v9
	v_exp_f32_e32 v14, v14
	v_exp_f32_e32 v8, v8
	v_add_f32_e32 v14, 1.0, v14
	v_add_f32_e32 v8, 1.0, v8
	v_rcp_f32_e32 v14, v14
	v_rcp_f32_e32 v15, v8
	s_nop 0
	v_pk_mul_f32 v[6:7], v[6:7], v[14:15]
	v_cvt_pk_bf16_f32 v14, v10, v11
	v_cvt_pk_bf16_f32 v15, v6, v7
	s_nop 0
	v_permlane32_swap_b32_e32 v12, v14
	v_permlane32_swap_b32_e32 v13, v15
	global_store_dwordx4 v[4:5], v[12:15], off offset:96
	s_setprio 0
	s_waitcnt lgkmcnt(0)
	s_barrier
	s_mov_b64 s[4:5], 0
